# v19 + filter weight-slice staging loop unrolled with all 8 global loads in flight
# speedup vs baseline: 1.0147x; 1.0029x over previous
; DI void phase_filter(const Params& p, int ch) {
;     ...
;     const float* w3 = p.hy_f_w3 + (size_t)dir * 64 * 2048 + c0;
;     for (int e = tid; e < 4096; e += NTHR) w3s[e] = w3[(size_t)(e >> 6) * 2048 + (e & 63)];
.LBB0_1402:
	v_mov_b32_e32 v218, v6
	v_mov_b32_e32 v219, v7
	v_ashrrev_i32_e32 v220, 6, v219
	v_ashrrev_i32_e32 v222, 6, v218
	v_ashrrev_i32_e32 v223, 31, v222
	v_ashrrev_i32_e32 v221, 31, v220
	v_lshlrev_b64 v[220:221], 13, v[220:221]
	v_lshlrev_b64 v[222:223], 13, v[222:223]
	v_lshl_add_u64 v[222:223], v[4:5], 0, v[222:223]
	v_lshl_add_u64 v[220:221], v[4:5], 0, v[220:221]
	global_load_dword v224, v[222:223], off
	global_load_dword v225, v[220:221], off
	v_add_u32_e32 v219, 0x400, v219
	v_add_u32_e32 v218, 0x400, v218
	v_ashrrev_i32_e32 v220, 6, v219
	v_ashrrev_i32_e32 v222, 6, v218
	v_ashrrev_i32_e32 v223, 31, v222
	v_ashrrev_i32_e32 v221, 31, v220
	v_lshlrev_b64 v[220:221], 13, v[220:221]
	v_lshlrev_b64 v[222:223], 13, v[222:223]
	v_lshl_add_u64 v[222:223], v[4:5], 0, v[222:223]
	v_lshl_add_u64 v[220:221], v[4:5], 0, v[220:221]
	global_load_dword v226, v[222:223], off
	global_load_dword v227, v[220:221], off
	v_add_u32_e32 v219, 0x400, v219
	v_add_u32_e32 v218, 0x400, v218
	v_ashrrev_i32_e32 v220, 6, v219
	v_ashrrev_i32_e32 v222, 6, v218
	v_ashrrev_i32_e32 v223, 31, v222
	v_ashrrev_i32_e32 v221, 31, v220
	v_lshlrev_b64 v[220:221], 13, v[220:221]
	v_lshlrev_b64 v[222:223], 13, v[222:223]
	v_lshl_add_u64 v[222:223], v[4:5], 0, v[222:223]
	v_lshl_add_u64 v[220:221], v[4:5], 0, v[220:221]
	global_load_dword v228, v[222:223], off
	global_load_dword v229, v[220:221], off
	v_add_u32_e32 v219, 0x400, v219
	v_add_u32_e32 v218, 0x400, v218
	v_ashrrev_i32_e32 v220, 6, v219
	v_ashrrev_i32_e32 v222, 6, v218
	v_ashrrev_i32_e32 v223, 31, v222
	v_ashrrev_i32_e32 v221, 31, v220
	v_lshlrev_b64 v[220:221], 13, v[220:221]
	v_lshlrev_b64 v[222:223], 13, v[222:223]
	v_lshl_add_u64 v[222:223], v[4:5], 0, v[222:223]
	v_lshl_add_u64 v[220:221], v[4:5], 0, v[220:221]
	global_load_dword v230, v[222:223], off
	global_load_dword v231, v[220:221], off
	v_add_u32_e32 v219, 0x400, v219
	v_add_u32_e32 v218, 0x400, v218
	v_ashrrev_i32_e32 v14, 6, v7
	v_ashrrev_i32_e32 v16, 6, v6
	v_ashrrev_i32_e32 v17, 31, v16
	v_ashrrev_i32_e32 v15, 31, v14
	v_lshlrev_b64 v[14:15], 13, v[14:15]
	v_lshlrev_b64 v[16:17], 13, v[16:17]
	v_lshl_add_u64 v[16:17], v[4:5], 0, v[16:17]
	v_lshl_add_u64 v[14:15], v[4:5], 0, v[14:15]
	s_nop 0
	v_add_u32_e32 v12, -2, v12
	s_nop 0
	v_add_u32_e32 v7, 0x400, v7
	v_add_u32_e32 v6, 0x400, v6
	s_nop 0
	s_waitcnt vmcnt(6)
	v_mov_b32_e32 v16, v224
	v_mov_b32_e32 v14, v225
	ds_write2st64_b32 v13, v16, v14 offset1:8
	v_add_u32_e32 v13, 0x1000, v13
	s_nop 0
	v_ashrrev_i32_e32 v14, 6, v7
	v_ashrrev_i32_e32 v16, 6, v6
	v_ashrrev_i32_e32 v17, 31, v16
	v_ashrrev_i32_e32 v15, 31, v14
	v_lshlrev_b64 v[14:15], 13, v[14:15]
	v_lshlrev_b64 v[16:17], 13, v[16:17]
	v_lshl_add_u64 v[16:17], v[4:5], 0, v[16:17]
	v_lshl_add_u64 v[14:15], v[4:5], 0, v[14:15]
	s_nop 0
	v_add_u32_e32 v12, -2, v12
	s_nop 0
	v_add_u32_e32 v7, 0x400, v7
	v_add_u32_e32 v6, 0x400, v6
	s_nop 0
	s_waitcnt vmcnt(4)
	v_mov_b32_e32 v16, v226
	v_mov_b32_e32 v14, v227
	ds_write2st64_b32 v13, v16, v14 offset1:8
	v_add_u32_e32 v13, 0x1000, v13
	s_nop 0
	v_ashrrev_i32_e32 v14, 6, v7
	v_ashrrev_i32_e32 v16, 6, v6
	v_ashrrev_i32_e32 v17, 31, v16
	v_ashrrev_i32_e32 v15, 31, v14
	v_lshlrev_b64 v[14:15], 13, v[14:15]
	v_lshlrev_b64 v[16:17], 13, v[16:17]
	v_lshl_add_u64 v[16:17], v[4:5], 0, v[16:17]
	v_lshl_add_u64 v[14:15], v[4:5], 0, v[14:15]
	s_nop 0
	v_add_u32_e32 v12, -2, v12
	s_nop 0
	v_add_u32_e32 v7, 0x400, v7
	v_add_u32_e32 v6, 0x400, v6
	s_nop 0
	s_waitcnt vmcnt(2)
	v_mov_b32_e32 v16, v228
	v_mov_b32_e32 v14, v229
	ds_write2st64_b32 v13, v16, v14 offset1:8
	v_add_u32_e32 v13, 0x1000, v13
	s_nop 0
	v_ashrrev_i32_e32 v14, 6, v7
	v_ashrrev_i32_e32 v16, 6, v6
	v_ashrrev_i32_e32 v17, 31, v16
	v_ashrrev_i32_e32 v15, 31, v14
	v_lshlrev_b64 v[14:15], 13, v[14:15]
	v_lshlrev_b64 v[16:17], 13, v[16:17]
	v_lshl_add_u64 v[16:17], v[4:5], 0, v[16:17]
	v_lshl_add_u64 v[14:15], v[4:5], 0, v[14:15]
	s_nop 0
	v_add_u32_e32 v12, -2, v12
	s_nop 0
	v_add_u32_e32 v7, 0x400, v7
	v_add_u32_e32 v6, 0x400, v6
	s_nop 0
	s_waitcnt vmcnt(0)
	v_mov_b32_e32 v16, v230
	v_mov_b32_e32 v14, v231
	ds_write2st64_b32 v13, v16, v14 offset1:8
	v_add_u32_e32 v13, 0x1000, v13
	s_nop 0
	s_mov_b64 s[20:21], exec
	s_or_b64 exec, exec, s[20:21]
	s_mov_b64 s[20:21], 0
	s_and_saveexec_b64 s[22:23], s[12:13]
	s_mov_b64 s[20:21], exec
	v_lshlrev_b32_e32 v7, 2, v9
	s_or_b64 exec, exec, s[22:23]
	s_orn2_b64 s[20:21], s[20:21], exec
	v_mov_b32_e32 v6, v9
